# ctx attention items moved from WGs 0-23 (which carry the extra g1m items) to WGs 32-55
# speedup vs baseline: 1.0076x; 1.0045x over previous
.LBB0_257:
	v_sub_f32_e32 v3, v224, v236
	v_min_f32_e32 v3, 0x42fc0000, v3
	s_mov_b32 s3, 0xc2fc0000
	v_cmp_gt_f32_e32 vcc, s3, v3
	v_mov_b32_e32 v0, v121
	s_nop 1
	v_permlane16_swap_b32_e32 v121, v0
	v_cndmask_b32_e32 v68, 0, v219, vcc
	v_add_f32_e32 v3, v3, v68
	v_add_f32_e32 v0, v121, v0
	v_exp_f32_e32 v3, v3
	v_mov_b32_e32 v2, v0
	s_nop 1
	v_permlane32_swap_b32_e32 v0, v2
	v_add_f32_e32 v0, v0, v2
	v_cndmask_b32_e32 v2, 0, v220, vcc
	v_ldexp_f32 v2, v3, v2
	v_add_f32_e32 v2, v2, v0
	v_cndmask_b32_e64 v0, v0, v2, s[18:19]
	v_div_scale_f32 v2, s[26:27], v0, v0, 1.0
	v_rcp_f32_e32 v3, v2
	s_nop 0
	v_fma_f32 v68, -v2, v3, 1.0
	v_fmac_f32_e32 v3, v68, v3
	v_div_scale_f32 v68, vcc, 1.0, v0, 1.0
	v_mul_f32_e32 v69, v68, v3
	v_fma_f32 v70, -v2, v69, v68
	v_fmac_f32_e32 v69, v70, v3
	v_fma_f32 v2, -v2, v69, v68
	v_div_fmas_f32 v2, v2, v3, v69
	v_div_fixup_f32 v0, v2, v0, 1.0
	v_mul_f32_e32 v2, v64, v0
	v_mul_f32_e32 v3, v65, v0
	v_cvt_pk_bf16_f32 v2, v2, v3
	v_mul_f32_e32 v3, v66, v0
	v_mul_f32_e32 v64, v67, v0
	v_cvt_pk_bf16_f32 v3, v3, v64
	ds_write_b64 v191, v[2:3]
	v_mul_f32_e32 v2, v60, v0
	v_mul_f32_e32 v3, v61, v0
	v_cvt_pk_bf16_f32 v2, v2, v3
	v_mul_f32_e32 v3, v62, v0
	v_mul_f32_e32 v60, v63, v0
	v_cvt_pk_bf16_f32 v3, v3, v60
	ds_write_b64 v192, v[2:3]
	v_mul_f32_e32 v2, v56, v0
	v_mul_f32_e32 v3, v57, v0
	v_cvt_pk_bf16_f32 v2, v2, v3
	v_mul_f32_e32 v3, v58, v0
	v_mul_f32_e32 v56, v59, v0
	v_cvt_pk_bf16_f32 v3, v3, v56
	ds_write_b64 v193, v[2:3]
	v_mul_f32_e32 v2, v52, v0
	v_mul_f32_e32 v3, v53, v0
	v_cvt_pk_bf16_f32 v2, v2, v3
	v_mul_f32_e32 v3, v54, v0
	v_mul_f32_e32 v52, v55, v0
	v_cvt_pk_bf16_f32 v3, v3, v52
	ds_write_b64 v194, v[2:3]
	v_mul_f32_e32 v2, v48, v0
	v_mul_f32_e32 v3, v49, v0
	v_cvt_pk_bf16_f32 v2, v2, v3
	v_mul_f32_e32 v3, v50, v0
	v_mul_f32_e32 v48, v51, v0
	v_cvt_pk_bf16_f32 v3, v3, v48
	ds_write_b64 v195, v[2:3]
	v_mul_f32_e32 v2, v44, v0
	v_mul_f32_e32 v3, v45, v0
	v_cvt_pk_bf16_f32 v2, v2, v3
	v_mul_f32_e32 v3, v46, v0
	v_mul_f32_e32 v44, v47, v0
	v_cvt_pk_bf16_f32 v3, v3, v44
	ds_write_b64 v196, v[2:3]
	v_mul_f32_e32 v2, v40, v0
	v_mul_f32_e32 v3, v41, v0
	v_cvt_pk_bf16_f32 v2, v2, v3
	v_mul_f32_e32 v3, v42, v0
	v_mul_f32_e32 v40, v43, v0
	v_cvt_pk_bf16_f32 v3, v3, v40
	ds_write_b64 v197, v[2:3]
	v_mul_f32_e32 v2, v36, v0
	v_mul_f32_e32 v3, v37, v0
	v_cvt_pk_bf16_f32 v2, v2, v3
	v_mul_f32_e32 v3, v38, v0
	v_sub_f32_e32 v38, v224, v128
	v_min_f32_e32 v38, 0x42fc0000, v38
	v_cmp_gt_f32_e32 vcc, s3, v38
	v_mov_b32_e32 v36, v120
	s_nop 1
	v_permlane16_swap_b32_e32 v120, v36
	v_cndmask_b32_e32 v40, 0, v219, vcc
	v_add_f32_e32 v38, v38, v40
	v_add_f32_e32 v36, v120, v36
	v_exp_f32_e32 v38, v38
	v_mov_b32_e32 v37, v36
	s_nop 1
	v_permlane32_swap_b32_e32 v36, v37
	v_add_f32_e32 v36, v36, v37
	v_cndmask_b32_e32 v37, 0, v220, vcc
	v_ldexp_f32 v37, v38, v37
	v_add_f32_e32 v37, v37, v36
	v_cndmask_b32_e64 v36, v36, v37, s[18:19]
	v_div_scale_f32 v37, s[18:19], v36, v36, 1.0
	v_rcp_f32_e32 v38, v37
	v_mul_f32_e32 v0, v39, v0
	v_cvt_pk_bf16_f32 v3, v3, v0
	ds_write_b64 v198, v[2:3]
	v_fma_f32 v0, -v37, v38, 1.0
	v_fmac_f32_e32 v38, v0, v38
	v_div_scale_f32 v0, vcc, 1.0, v36, 1.0
	v_mul_f32_e32 v2, v0, v38
	v_fma_f32 v3, -v37, v2, v0
	v_fmac_f32_e32 v2, v3, v38
	v_fma_f32 v0, -v37, v2, v0
	v_div_fmas_f32 v0, v0, v38, v2
	v_div_fixup_f32 v0, v0, v36, 1.0
	v_mul_f32_e32 v2, v32, v0
	v_mul_f32_e32 v3, v33, v0
	v_cvt_pk_bf16_f32 v2, v2, v3
	v_mul_f32_e32 v3, v34, v0
	v_mul_f32_e32 v32, v35, v0
	v_cvt_pk_bf16_f32 v3, v3, v32
	ds_write_b64 v191, v[2:3] offset:4096
	v_mul_f32_e32 v2, v28, v0
	v_mul_f32_e32 v3, v29, v0
	v_cvt_pk_bf16_f32 v2, v2, v3
	v_mul_f32_e32 v3, v30, v0
	v_mul_f32_e32 v28, v31, v0
	v_cvt_pk_bf16_f32 v3, v3, v28
	ds_write_b64 v192, v[2:3] offset:4096
	v_mul_f32_e32 v2, v24, v0
	v_mul_f32_e32 v3, v25, v0
	v_cvt_pk_bf16_f32 v2, v2, v3
	v_mul_f32_e32 v3, v26, v0
	v_mul_f32_e32 v24, v27, v0
	v_cvt_pk_bf16_f32 v3, v3, v24
	ds_write_b64 v193, v[2:3] offset:4096
	v_mul_f32_e32 v2, v20, v0
	v_mul_f32_e32 v3, v21, v0
	v_cvt_pk_bf16_f32 v2, v2, v3
	v_mul_f32_e32 v3, v22, v0
	v_mul_f32_e32 v20, v23, v0
	v_cvt_pk_bf16_f32 v3, v3, v20
	ds_write_b64 v194, v[2:3] offset:4096
	v_mul_f32_e32 v2, v16, v0
	v_mul_f32_e32 v3, v17, v0
	v_cvt_pk_bf16_f32 v2, v2, v3
	v_mul_f32_e32 v3, v18, v0
	v_mul_f32_e32 v16, v19, v0
	v_cvt_pk_bf16_f32 v3, v3, v16
	ds_write_b64 v195, v[2:3] offset:4096
	v_mul_f32_e32 v2, v12, v0
	v_mul_f32_e32 v3, v13, v0
	v_cvt_pk_bf16_f32 v2, v2, v3
	v_mul_f32_e32 v3, v14, v0
	v_mul_f32_e32 v12, v15, v0
	v_cvt_pk_bf16_f32 v3, v3, v12
	ds_write_b64 v196, v[2:3] offset:4096
	v_mul_f32_e32 v2, v8, v0
	v_mul_f32_e32 v3, v9, v0
	v_cvt_pk_bf16_f32 v2, v2, v3
	v_mul_f32_e32 v3, v10, v0
	v_mul_f32_e32 v8, v11, v0
	v_cvt_pk_bf16_f32 v3, v3, v8
	ds_write_b64 v197, v[2:3] offset:4096
	v_mul_f32_e32 v2, v4, v0
	v_mul_f32_e32 v3, v5, v0
	v_cvt_pk_bf16_f32 v2, v2, v3
	v_mul_f32_e32 v3, v6, v0
	v_mul_f32_e32 v0, v7, v0
	v_cvt_pk_bf16_f32 v3, v3, v0
	ds_write_b64 v198, v[2:3] offset:4096
	ds_read_b128 v[2:5], v199
	v_add_u32_e32 v6, s56, v148
	s_ashr_i32 s3, s2, 31
	v_ashrrev_i32_e32 v7, 31, v6
	v_lshl_add_u64 v[10:11], s[2:3], 1, v[134:135]
	v_lshlrev_b64 v[6:7], 12, v[6:7]
	v_lshl_add_u64 v[12:13], v[10:11], 0, v[6:7]
	ds_read_b128 v[6:9], v200
	s_waitcnt lgkmcnt(1)
	global_store_dwordx4 v[12:13], v[2:5], off
	s_nop 1
	v_add_u32_e32 v2, s56, v151
	v_ashrrev_i32_e32 v3, 31, v2
	v_lshlrev_b64 v[2:3], 12, v[2:3]
	v_lshl_add_u64 v[2:3], v[10:11], 0, v[2:3]
	s_waitcnt lgkmcnt(0)
	global_store_dwordx4 v[2:3], v[6:9], off
	ds_read_b128 v[2:5], v201
	s_nop 0
	v_add_u32_e32 v6, s56, v153
	v_ashrrev_i32_e32 v7, 31, v6
	v_lshlrev_b64 v[6:7], 12, v[6:7]
	v_lshl_add_u64 v[12:13], v[10:11], 0, v[6:7]
	ds_read_b128 v[6:9], v202
	s_waitcnt lgkmcnt(1)
	global_store_dwordx4 v[12:13], v[2:5], off
	s_nop 1
	v_add_u32_e32 v2, s56, v157
	v_ashrrev_i32_e32 v3, 31, v2
	v_lshlrev_b64 v[2:3], 12, v[2:3]
	v_lshl_add_u64 v[2:3], v[10:11], 0, v[2:3]
	s_waitcnt lgkmcnt(0)
	global_store_dwordx4 v[2:3], v[6:9], off
	ds_read_b128 v[2:5], v203
	s_nop 0
	v_add_u32_e32 v6, s56, v179
	v_ashrrev_i32_e32 v7, 31, v6
	v_lshlrev_b64 v[6:7], 12, v[6:7]
	v_lshl_add_u64 v[12:13], v[10:11], 0, v[6:7]
	ds_read_b128 v[6:9], v204
	s_waitcnt lgkmcnt(1)
	global_store_dwordx4 v[12:13], v[2:5], off
	s_nop 1
	v_add_u32_e32 v2, s56, v180
	v_ashrrev_i32_e32 v3, 31, v2
	v_lshlrev_b64 v[2:3], 12, v[2:3]
	v_lshl_add_u64 v[2:3], v[10:11], 0, v[2:3]
	s_waitcnt lgkmcnt(0)
	global_store_dwordx4 v[2:3], v[6:9], off
	ds_read_b128 v[2:5], v205
	s_nop 0
	v_add_u32_e32 v6, s56, v181
	v_ashrrev_i32_e32 v7, 31, v6
	v_lshlrev_b64 v[6:7], 12, v[6:7]
	v_lshl_add_u64 v[12:13], v[10:11], 0, v[6:7]
	ds_read_b128 v[6:9], v223
	s_waitcnt lgkmcnt(1)
	global_store_dwordx4 v[12:13], v[2:5], off
	s_nop 1
	v_add_u32_e32 v2, s56, v182
	v_ashrrev_i32_e32 v3, 31, v2
	v_lshlrev_b64 v[2:3], 12, v[2:3]
	v_lshl_add_u64 v[2:3], v[10:11], 0, v[2:3]
	s_waitcnt lgkmcnt(0)
	global_store_dwordx4 v[2:3], v[6:9], off
	s_load_dword s2, s[98:99], 0x10
	s_waitcnt lgkmcnt(0)
	s_lshr_b32 s2, s2, 16
	s_cmp_lg_u32 s2, 0
	s_cselect_b64 s[2:3], -1, 0
	s_cmp_lg_u64 s[2:3], 0
	v_readlane_b32 s2, v255, 0
	s_nop 1
	s_addc_u32 s2, s2, s28
	v_writelane_b32 v255, s2, 0
	s_cmpk_lt_u32 s2, 0x600
	s_cbranch_scc1 .Lqa_norm
	s_cmpk_lt_u32 s2, 0x620
	s_cbranch_scc1 .LBB0_352
	s_sub_i32 s2, s2, 32
	s_cmp_ge_i32 s2, s6
	s_cbranch_scc1 .LBB0_352
	s_mov_b32 s53, s2
	s_branch .LBB0_258
.Lqa_norm:
	s_cmp_ge_i32 s2, s6
	s_cbranch_scc1 .LBB0_352
	s_and_b32 s3, s2, 7
	s_lshl_b32 s3, s3, 5
	s_bfe_u32 s53, s2, 0x50003
	s_or_b32 s3, s3, s53
	s_and_b32 s53, s2, 0xffffff00
	s_or_b32 s3, s3, s53
	s_cmpk_lt_u32 s2, 0x600
	s_cselect_b32 s53, s3, s2
